# v25 plus SWA V fragments loaded as 16-byte pieces (4 loads instead of 8 per key block) with a permlane32 exchange in front of the PV MFMAs
# speedup vs baseline: 1.0390x; 1.0161x over previous
.LBB0_253:
	v_lshrrev_b32_e32 v0, 3, v88
	v_and_b32_e32 v2, 4, v88
	v_and_b32_e32 v1, 6, v0
	v_and_or_b32 v0, v0, 8, v2
	v_lshrrev_b32_e32 v2, 1, v88
	v_ashrrev_i32_e32 v33, 8, v88
	v_and_b32_e32 v34, 4, v2
	v_lshrrev_b32_e32 v0, 2, v0
	v_and_or_b32 v35, v33, -8, v1
	v_and_b32_e32 v1, 0x780, v88
	v_or_b32_e32 v36, v0, v34
	v_lshlrev_b32_e32 v0, 5, v88
	v_and_or_b32 v0, v0, s54, v1
	v_lshlrev_b32_e32 v1, 10, v35
	v_or3_b32 v78, v0, v89, v1
	v_lshrrev_b32_e32 v0, 5, v0
	v_min_u32_e32 v2, 59, v0
	v_lshlrev_b32_e32 v1, 6, v36
	v_sub_u32_e64 v71, v0, 4 clamp
	v_add_u32_e32 v73, 5, v2
	v_ashrrev_i32_e32 v79, 31, v78
	v_cmp_lt_u32_e32 vcc, v71, v73
	v_lshlrev_b32_e32 v80, 1, v1
	v_mov_b32_e32 v15, v65
	v_mov_b32_e32 v14, v65
	v_mov_b32_e32 v13, v65
	v_mov_b32_e32 v12, v65
	v_mov_b32_e32 v11, v65
	v_mov_b32_e32 v10, v65
	v_mov_b32_e32 v9, v65
	v_mov_b32_e32 v8, v65
	v_mov_b32_e32 v7, v65
	v_mov_b32_e32 v6, v65
	v_mov_b32_e32 v5, v65
	v_mov_b32_e32 v4, v65
	v_mov_b32_e32 v3, v65
	v_mov_b32_e32 v2, v65
	v_mov_b32_e32 v1, v65
	v_mov_b32_e32 v0, v65
	v_mov_b32_e32 v31, v65
	v_mov_b32_e32 v30, v65
	v_mov_b32_e32 v29, v65
	v_mov_b32_e32 v28, v65
	v_mov_b32_e32 v27, v65
	v_mov_b32_e32 v26, v65
	v_mov_b32_e32 v25, v65
	v_mov_b32_e32 v24, v65
	v_mov_b32_e32 v23, v65
	v_mov_b32_e32 v22, v65
	v_mov_b32_e32 v21, v65
	v_mov_b32_e32 v20, v65
	v_mov_b32_e32 v19, v65
	v_mov_b32_e32 v18, v65
	v_mov_b32_e32 v17, v65
	v_mov_b32_e32 v16, v65
	v_mov_b32_e32 v32, v90
	s_and_saveexec_b64 s[48:49], vcc
	s_cbranch_execz .LBB0_252
	v_mov_b64_e32 v[0:1], s[38:39]
	v_mad_i64_i32 v[0:1], s[0:1], v78, s55, v[0:1]
	v_mov_b32_e32 v81, v65
	v_lshl_add_u64 v[0:1], v[0:1], 0, v[80:81]
	v_mov_b32_e32 v77, v65
	v_lshl_add_u64 v[0:1], v[0:1], 0, v[76:77]
	global_load_dwordx4 v[48:51], v[0:1], off offset:3072
	global_load_dwordx4 v[52:55], v[0:1], off offset:3104
	global_load_dwordx4 v[56:59], v[0:1], off offset:3136
	global_load_dwordx4 v[60:63], v[0:1], off offset:3168
	v_readlane_b32 s0, v254, 6
	v_lshlrev_b32_e32 v0, 2, v36
	v_readlane_b32 s12, v254, 18
	v_readlane_b32 s13, v254, 19
	v_lshrrev_b32_e32 v1, 1, v35
	v_mul_i32_i24_e32 v1, 10, v1
	v_mov_b32_e32 v69, v65
	v_lshlrev_b32_e32 v64, 5, v34
	v_lshl_add_u64 v[82:83], s[38:39], 0, v[64:65]
	global_load_dword v81, v0, s[12:13]
	v_and_b32_e32 v0, 0x60, v92
	v_and_or_b32 v2, v88, s53, v0
	v_lshrrev_b32_e32 v0, 5, v2
	v_min_u32_e32 v0, 4, v0
	v_lshlrev_b32_e32 v3, 5, v0
	v_lshlrev_b32_e32 v0, 7, v88
	v_and_b32_e32 v5, 0x1800, v0
	v_lshrrev_b32_e32 v0, 2, v34
	v_or_b32_e32 v0, v1, v0
	v_add_u32_e32 v0, 8, v0
	v_ashrrev_i32_e32 v1, 31, v0
	v_lshlrev_b64 v[0:1], 18, v[0:1]
	v_lshl_add_u64 v[0:1], v[66:67], 0, v[0:1]
	v_lshl_add_u64 v[84:85], v[0:1], 0, v[68:69]
	v_lshlrev_b32_e32 v0, 10, v33
	v_and_b32_e32 v0, 0xffffe000, v0
	v_or3_b32 v0, v0, v5, v2
	v_sub_u32_e32 v4, v2, v3
	v_sub_u32_e32 v69, v0, v3
	v_mov_b32_e32 v0, 0
	v_add_u32_e32 v75, v91, v3
	v_lshl_add_u64 v[86:87], v[84:85], 0, s[40:41]
	s_mov_b64 s[50:51], 0
	v_mov_b32_e32 v64, v4
	v_mov_b32_e32 v32, v90
	v_mov_b32_e32 v1, v0
	v_mov_b32_e32 v2, v0
	v_mov_b32_e32 v3, v0
	v_mov_b32_e32 v4, v0
	v_mov_b32_e32 v5, v0
	v_mov_b32_e32 v6, v0
	v_mov_b32_e32 v7, v0
	v_mov_b32_e32 v8, v0
	v_mov_b32_e32 v9, v0
	v_mov_b32_e32 v10, v0
	v_mov_b32_e32 v11, v0
	v_mov_b32_e32 v12, v0
	v_mov_b32_e32 v13, v0
	v_mov_b32_e32 v14, v0
	v_mov_b32_e32 v15, v0
	v_mov_b32_e32 v16, v0
	v_mov_b32_e32 v17, v0
	v_mov_b32_e32 v18, v0
	v_mov_b32_e32 v19, v0
	v_mov_b32_e32 v20, v0
	v_mov_b32_e32 v21, v0
	v_mov_b32_e32 v22, v0
	v_mov_b32_e32 v23, v0
	v_mov_b32_e32 v24, v0
	v_mov_b32_e32 v25, v0
	v_mov_b32_e32 v26, v0
	v_mov_b32_e32 v27, v0
	v_mov_b32_e32 v28, v0
	v_mov_b32_e32 v29, v0
	v_mov_b32_e32 v30, v0
	v_mov_b32_e32 v31, v0
	v_readlane_b32 s1, v254, 7
	v_readlane_b32 s2, v254, 8
	v_readlane_b32 s3, v254, 9
	v_readlane_b32 s4, v254, 10
	v_readlane_b32 s5, v254, 11
	v_readlane_b32 s6, v254, 12
	v_readlane_b32 s7, v254, 13
	v_readlane_b32 s8, v254, 14
	v_readlane_b32 s9, v254, 15
	v_readlane_b32 s10, v254, 16
	v_readlane_b32 s11, v254, 17
	v_readlane_b32 s14, v254, 20
	v_readlane_b32 s15, v254, 21
	v_lshrrev_b32_e32 v164, 5, v179
	v_lshlrev_b32_e32 v164, 3, v164
	v_mov_b32_e32 v165, 0
.LBB0_255:
	v_add_u32_e32 v36, v89, v69
	v_mov_b32_e32 v94, v32
	v_lshlrev_b64 v[32:33], 1, v[64:65]
	v_mad_i64_i32 v[36:37], s[0:1], v36, s55, v[82:83]
	v_add_u32_e32 v34, 16, v64
	v_mov_b32_e32 v35, v65
	v_lshl_add_u64 v[38:39], v[84:85], 0, v[32:33]
	v_lshl_add_u64 v[38:39], v[38:39], 0, v[164:165]
	v_lshl_add_u64 v[32:33], v[86:87], 0, v[32:33]
	v_lshl_add_u64 v[32:33], v[32:33], 0, v[164:165]
	v_lshl_add_u64 v[36:37], v[36:37], 0, v[76:77]
	v_lshl_add_u64 v[34:35], v[34:35], 1, v[86:87]
	v_lshl_add_u64 v[34:35], v[34:35], 0, v[164:165]
	global_load_dwordx4 v[96:99], v[38:39], off
	global_load_dwordx4 v[100:103], v[38:39], off offset:32
	global_load_dwordx4 v[104:107], v[32:33], off
	global_load_dwordx4 v[108:111], v[34:35], off
	v_add_co_u32_e64 v32, s[0:1], s33, v36
	v_lshl_add_u64 v[120:121], v[36:37], 0, s[42:43]
	s_nop 0
	v_addc_co_u32_e64 v33, s[0:1], 0, v37, s[0:1]
	global_load_dwordx4 v[32:35], v[32:33], off
	s_nop 0
	global_load_dwordx4 v[112:115], v[120:121], off offset:32
	global_load_dwordx4 v[116:119], v[120:121], off offset:96
	v_add_u32_e32 v40, v89, v75
	v_add_u32_e32 v154, s56, v40
	v_add_u32_e32 v154, -1, v154
	v_lshl_add_u32 v156, s56, 1, -1
	global_load_dwordx4 v[120:123], v[120:121], off offset:64
	s_waitcnt vmcnt(19)
	s_waitcnt vmcnt(18)
	v_subrev_u32_e32 v149, 0, v154
	v_subrev_u32_e32 v150, 1, v154
	v_subrev_u32_e32 v151, 2, v154
	v_add_u32_e32 v71, 1, v71
	v_cmp_ge_u32_e32 vcc, v71, v73
	v_subrev_u32_e32 v95, 3, v154
	s_or_b64 s[50:51], vcc, s[50:51]
	v_cmp_gt_u32_e32 vcc, v156, v150
	v_cmp_gt_u32_e64 s[2:3], v156, v95
	v_cmp_gt_u32_e64 s[28:29], v156, v149
	v_cmp_gt_u32_e64 s[0:1], v156, v151
	v_subrev_u32_e32 v124, 16, v154
	v_cmp_gt_u32_e64 s[12:13], v156, v124
	v_subrev_u32_e32 v75, 32, v75
	v_add_u32_e32 v64, 32, v64
	v_add_u32_e32 v69, 32, v69
	s_waitcnt vmcnt(3)
	v_mfma_f32_32x32x16_bf16 v[32:47], v[32:35], v[48:51], 0
	s_waitcnt vmcnt(2)
	v_mfma_f32_32x32x16_bf16 v[32:47], v[112:115], v[52:55], v[32:47]
	v_subrev_u32_e32 v112, 8, v154
	v_cmp_gt_u32_e64 s[4:5], v156, v112
	v_subrev_u32_e32 v113, 9, v154
	v_subrev_u32_e32 v114, 10, v154
	v_subrev_u32_e32 v115, 11, v154
	v_cmp_gt_u32_e64 s[6:7], v156, v113
	v_cmp_gt_u32_e64 s[8:9], v156, v114
	s_waitcnt vmcnt(0)
	v_mfma_f32_32x32x16_bf16 v[32:47], v[120:123], v[56:59], v[32:47]
	v_subrev_u32_e32 v125, 17, v154
	v_cmp_gt_u32_e64 s[10:11], v156, v115
	v_subrev_u32_e32 v120, 18, v154
	v_subrev_u32_e32 v121, 19, v154
	v_cmp_gt_u32_e64 s[14:15], v156, v125
	v_subrev_u32_e32 v122, 24, v154
	v_subrev_u32_e32 v123, 25, v154
	v_mfma_f32_32x32x16_bf16 v[32:47], v[116:119], v[60:63], v[32:47]
	v_cmp_gt_u32_e64 s[16:17], v156, v120
	v_cmp_gt_u32_e64 s[18:19], v156, v121
	v_subrev_u32_e32 v126, 26, v154
	v_subrev_u32_e32 v127, 27, v154
	v_cmp_gt_u32_e64 s[20:21], v156, v122
	v_cmp_gt_u32_e64 s[22:23], v156, v123
	v_cmp_gt_u32_e64 s[24:25], v156, v126
	s_nop 4
	v_max_f32_e32 v95, v32, v32
	v_cndmask_b32_e32 v112, v93, v33, vcc
	v_max_f32_e32 v95, 0xf149f2ca, v95
	v_max_f32_e32 v112, v112, v112
	v_cndmask_b32_e64 v95, v93, v95, s[28:29]
	v_cndmask_b32_e64 v113, v93, v34, s[0:1]
	v_cndmask_b32_e64 v114, v93, v35, s[2:3]
	v_max_f32_e32 v95, v95, v112
	v_cndmask_b32_e64 v115, v93, v36, s[4:5]
	v_cndmask_b32_e64 v116, v93, v37, s[6:7]
	v_max3_f32 v95, v95, v113, v114
	v_cndmask_b32_e64 v117, v93, v38, s[8:9]
	v_cndmask_b32_e64 v118, v93, v39, s[10:11]
	v_max3_f32 v95, v95, v115, v116
	v_cndmask_b32_e64 v119, v93, v40, s[12:13]
	v_cndmask_b32_e64 v120, v93, v41, s[14:15]
	v_max3_f32 v95, v95, v117, v118
	v_cndmask_b32_e64 v121, v93, v42, s[16:17]
	v_cndmask_b32_e64 v122, v93, v43, s[18:19]
	v_max3_f32 v95, v95, v119, v120
	v_cmp_gt_u32_e64 s[26:27], v156, v127
	v_cndmask_b32_e64 v123, v93, v44, s[20:21]
	v_cndmask_b32_e64 v124, v93, v45, s[22:23]
	v_max3_f32 v95, v95, v121, v122
	v_cndmask_b32_e64 v125, v93, v46, s[24:25]
	v_cndmask_b32_e64 v126, v93, v47, s[26:27]
	v_max3_f32 v95, v95, v123, v124
	v_max3_f32 v95, v95, v125, v126
	v_mov_b32_e32 v112, v95
	s_nop 1
	v_permlane32_swap_b32_e32 v95, v112
	v_max3_f32 v95, v81, v95, v112
	v_sub_f32_e32 v32, v32, v95
	v_sub_f32_e32 v33, v33, v95
	v_sub_f32_e32 v34, v34, v95
	v_sub_f32_e32 v35, v35, v95
	v_sub_f32_e32 v36, v36, v95
	v_sub_f32_e32 v37, v37, v95
	v_sub_f32_e32 v38, v38, v95
	v_sub_f32_e32 v39, v39, v95
	v_sub_f32_e32 v112, v81, v95
	v_mul_f32_e32 v32, 0x3fb8aa3b, v32
	v_mul_f32_e32 v33, 0x3fb8aa3b, v33
	v_mul_f32_e32 v34, 0x3fb8aa3b, v34
	v_mul_f32_e32 v35, 0x3fb8aa3b, v35
	v_mul_f32_e32 v36, 0x3fb8aa3b, v36
	v_mul_f32_e32 v37, 0x3fb8aa3b, v37
	v_mul_f32_e32 v38, 0x3fb8aa3b, v38
	v_mul_f32_e32 v39, 0x3fb8aa3b, v39
	v_sub_f32_e32 v40, v40, v95
	v_sub_f32_e32 v41, v41, v95
	v_sub_f32_e32 v42, v42, v95
	v_sub_f32_e32 v43, v43, v95
	v_sub_f32_e32 v44, v44, v95
	v_sub_f32_e32 v45, v45, v95
	v_sub_f32_e32 v46, v46, v95
	v_sub_f32_e32 v47, v47, v95
	v_mov_b32_e32 v81, v95
	v_mul_f32_e32 v95, 0x3fb8aa3b, v112
	v_exp_f32_e32 v32, v32
	v_exp_f32_e32 v33, v33
	v_exp_f32_e32 v34, v34
	v_exp_f32_e32 v35, v35
	v_exp_f32_e32 v112, v36
	v_exp_f32_e32 v37, v37
	v_exp_f32_e32 v38, v38
	v_exp_f32_e32 v39, v39
	v_exp_f32_e32 v36, v95
	v_cndmask_b32_e64 v95, 0, v32, s[28:29]
	v_cndmask_b32_e32 v113, 0, v33, vcc
	v_cndmask_b32_e64 v114, 0, v34, s[0:1]
	v_cndmask_b32_e64 v115, 0, v35, s[2:3]
	v_cndmask_b32_e64 v112, 0, v112, s[4:5]
	v_cndmask_b32_e64 v37, 0, v37, s[6:7]
	v_cndmask_b32_e64 v38, 0, v38, s[8:9]
	v_cndmask_b32_e64 v39, 0, v39, s[10:11]
	v_pk_mul_f32 v[14:15], v[14:15], v[36:37] op_sel_hi:[1,0]
	v_pk_mul_f32 v[12:13], v[12:13], v[36:37] op_sel_hi:[1,0]
	v_pk_mul_f32 v[10:11], v[10:11], v[36:37] op_sel_hi:[1,0]
	v_pk_mul_f32 v[8:9], v[8:9], v[36:37] op_sel_hi:[1,0]
	v_pk_mul_f32 v[6:7], v[6:7], v[36:37] op_sel_hi:[1,0]
	v_pk_mul_f32 v[4:5], v[4:5], v[36:37] op_sel_hi:[1,0]
	v_pk_mul_f32 v[2:3], v[2:3], v[36:37] op_sel_hi:[1,0]
	v_pk_mul_f32 v[0:1], v[0:1], v[36:37] op_sel_hi:[1,0]
	v_pk_mul_f32 v[30:31], v[30:31], v[36:37] op_sel_hi:[1,0]
	v_cvt_pk_bf16_f32 v32, v95, v113
	v_cvt_pk_bf16_f32 v33, v114, v115
	v_cvt_pk_bf16_f32 v34, v112, v37
	v_cvt_pk_bf16_f32 v35, v38, v39
	v_pk_mul_f32 v[28:29], v[28:29], v[36:37] op_sel_hi:[1,0]
	v_pk_mul_f32 v[26:27], v[26:27], v[36:37] op_sel_hi:[1,0]
	v_pk_mul_f32 v[24:25], v[24:25], v[36:37] op_sel_hi:[1,0]
	v_pk_mul_f32 v[22:23], v[22:23], v[36:37] op_sel_hi:[1,0]
	v_pk_mul_f32 v[20:21], v[20:21], v[36:37] op_sel_hi:[1,0]
	v_pk_mul_f32 v[18:19], v[18:19], v[36:37] op_sel_hi:[1,0]
	v_pk_mul_f32 v[16:17], v[16:17], v[36:37] op_sel_hi:[1,0]
	v_add_f32_e32 v95, 0, v95
	v_permlane32_swap_b32_e32 v96, v98
	v_permlane32_swap_b32_e32 v97, v99
	s_nop 1
	v_mfma_f32_32x32x16_bf16 v[0:15], v[96:99], v[32:35], v[0:15]
	v_add_f32_e32 v95, v113, v95
	v_mul_f32_e32 v40, 0x3fb8aa3b, v40
	v_mul_f32_e32 v41, 0x3fb8aa3b, v41
	v_mul_f32_e32 v42, 0x3fb8aa3b, v42
	v_mul_f32_e32 v43, 0x3fb8aa3b, v43
	v_mul_f32_e32 v44, 0x3fb8aa3b, v44
	v_mul_f32_e32 v45, 0x3fb8aa3b, v45
	v_permlane32_swap_b32_e32 v104, v106
	v_permlane32_swap_b32_e32 v105, v107
	s_nop 1
	v_mfma_f32_32x32x16_bf16 v[16:31], v[104:107], v[32:35], v[16:31]
	v_mul_f32_e32 v46, 0x3fb8aa3b, v46
	v_mul_f32_e32 v47, 0x3fb8aa3b, v47
	v_add_f32_e32 v95, v114, v95
	v_exp_f32_e32 v40, v40
	v_exp_f32_e32 v41, v41
	v_exp_f32_e32 v42, v42
	v_exp_f32_e32 v43, v43
	v_exp_f32_e32 v44, v44
	v_exp_f32_e32 v45, v45
	v_exp_f32_e32 v46, v46
	v_exp_f32_e32 v47, v47
	v_add_f32_e32 v95, v115, v95
	v_add_f32_e32 v95, v112, v95
	v_add_f32_e32 v37, v37, v95
	v_add_f32_e32 v37, v38, v37
	v_cndmask_b32_e64 v40, 0, v40, s[12:13]
	v_cndmask_b32_e64 v41, 0, v41, s[14:15]
	v_cndmask_b32_e64 v42, 0, v42, s[16:17]
	v_cndmask_b32_e64 v43, 0, v43, s[18:19]
	v_cndmask_b32_e64 v44, 0, v44, s[20:21]
	v_cndmask_b32_e64 v45, 0, v45, s[22:23]
	v_cndmask_b32_e64 v46, 0, v46, s[24:25]
	v_cndmask_b32_e64 v47, 0, v47, s[26:27]
	v_add_f32_e32 v37, v39, v37
	v_cvt_pk_bf16_f32 v32, v40, v41
	v_cvt_pk_bf16_f32 v33, v42, v43
	v_cvt_pk_bf16_f32 v34, v44, v45
	v_cvt_pk_bf16_f32 v35, v46, v47
	v_add_f32_e32 v37, v40, v37
	v_add_f32_e32 v37, v41, v37
	v_permlane32_swap_b32_e32 v100, v102
	v_permlane32_swap_b32_e32 v101, v103
	s_nop 1
	v_mfma_f32_32x32x16_bf16 v[0:15], v[100:103], v[32:35], v[0:15]
	v_permlane32_swap_b32_e32 v108, v110
	v_permlane32_swap_b32_e32 v109, v111
	s_nop 1
	v_mfma_f32_32x32x16_bf16 v[16:31], v[108:111], v[32:35], v[16:31]
	v_add_f32_e32 v32, v42, v37
	v_add_f32_e32 v32, v43, v32
	v_add_f32_e32 v32, v44, v32
	v_add_f32_e32 v32, v45, v32
	v_add_f32_e32 v32, v46, v32
	v_add_f32_e32 v32, v47, v32
	v_fmac_f32_e32 v32, v94, v36
	s_andn2_b64 exec, exec, s[50:51]
	s_cbranch_execnz .LBB0_255
	s_or_b64 exec, exec, s[50:51]
	s_branch .LBB0_252

.LBB0_838:
	v_lshrrev_b32_e32 v0, 3, v88
	v_and_b32_e32 v2, 4, v88
	v_and_b32_e32 v1, 6, v0
	v_and_or_b32 v0, v0, 8, v2
	v_lshrrev_b32_e32 v2, 1, v88
	v_ashrrev_i32_e32 v33, 8, v88
	v_and_b32_e32 v34, 4, v2
	v_lshrrev_b32_e32 v0, 2, v0
	v_and_or_b32 v35, v33, -8, v1
	v_and_b32_e32 v1, 0x780, v88
	v_or_b32_e32 v36, v0, v34
	v_lshlrev_b32_e32 v0, 5, v88
	v_and_or_b32 v0, v0, s54, v1
	v_lshlrev_b32_e32 v1, 10, v35
	v_or3_b32 v78, v0, v89, v1
	v_lshrrev_b32_e32 v0, 5, v0
	v_min_u32_e32 v2, 59, v0
	v_lshlrev_b32_e32 v1, 6, v36
	v_sub_u32_e64 v71, v0, 4 clamp
	v_add_u32_e32 v73, 5, v2
	v_ashrrev_i32_e32 v79, 31, v78
	v_cmp_lt_u32_e32 vcc, v71, v73
	v_lshlrev_b32_e32 v80, 1, v1
	v_mov_b32_e32 v15, v65
	v_mov_b32_e32 v14, v65
	v_mov_b32_e32 v13, v65
	v_mov_b32_e32 v12, v65
	v_mov_b32_e32 v11, v65
	v_mov_b32_e32 v10, v65
	v_mov_b32_e32 v9, v65
	v_mov_b32_e32 v8, v65
	v_mov_b32_e32 v7, v65
	v_mov_b32_e32 v6, v65
	v_mov_b32_e32 v5, v65
	v_mov_b32_e32 v4, v65
	v_mov_b32_e32 v3, v65
	v_mov_b32_e32 v2, v65
	v_mov_b32_e32 v1, v65
	v_mov_b32_e32 v0, v65
	v_mov_b32_e32 v31, v65
	v_mov_b32_e32 v30, v65
	v_mov_b32_e32 v29, v65
	v_mov_b32_e32 v28, v65
	v_mov_b32_e32 v27, v65
	v_mov_b32_e32 v26, v65
	v_mov_b32_e32 v25, v65
	v_mov_b32_e32 v24, v65
	v_mov_b32_e32 v23, v65
	v_mov_b32_e32 v22, v65
	v_mov_b32_e32 v21, v65
	v_mov_b32_e32 v20, v65
	v_mov_b32_e32 v19, v65
	v_mov_b32_e32 v18, v65
	v_mov_b32_e32 v17, v65
	v_mov_b32_e32 v16, v65
	v_mov_b32_e32 v32, v90
	s_and_saveexec_b64 s[48:49], vcc
	s_cbranch_execz .LBB0_837
	v_mov_b64_e32 v[0:1], s[38:39]
	v_mad_i64_i32 v[0:1], s[0:1], v78, s55, v[0:1]
	v_mov_b32_e32 v81, v65
	v_lshl_add_u64 v[0:1], v[0:1], 0, v[80:81]
	v_mov_b32_e32 v77, v65
	v_lshl_add_u64 v[0:1], v[0:1], 0, v[76:77]
	global_load_dwordx4 v[48:51], v[0:1], off offset:3072
	global_load_dwordx4 v[52:55], v[0:1], off offset:3104
	global_load_dwordx4 v[56:59], v[0:1], off offset:3136
	global_load_dwordx4 v[60:63], v[0:1], off offset:3168
	v_readlane_b32 s0, v254, 6
	v_lshlrev_b32_e32 v0, 2, v36
	v_readlane_b32 s12, v254, 18
	v_readlane_b32 s13, v254, 19
	v_lshrrev_b32_e32 v1, 1, v35
	v_mul_i32_i24_e32 v1, 10, v1
	v_mov_b32_e32 v69, v65
	v_lshlrev_b32_e32 v64, 5, v34
	v_lshl_add_u64 v[82:83], s[38:39], 0, v[64:65]
	global_load_dword v81, v0, s[12:13] offset:32
	v_and_b32_e32 v0, 0x60, v92
	v_and_or_b32 v2, v88, s53, v0
	v_lshrrev_b32_e32 v0, 5, v2
	v_min_u32_e32 v0, 4, v0
	v_lshlrev_b32_e32 v3, 5, v0
	v_lshlrev_b32_e32 v0, 7, v88
	v_and_b32_e32 v5, 0x1800, v0
	v_lshrrev_b32_e32 v0, 2, v34
	v_or_b32_e32 v0, v1, v0
	v_add_u32_e32 v0, 8, v0
	v_ashrrev_i32_e32 v1, 31, v0
	v_lshlrev_b64 v[0:1], 18, v[0:1]
	v_lshl_add_u64 v[0:1], v[66:67], 0, v[0:1]
	v_lshl_add_u64 v[84:85], v[0:1], 0, v[68:69]
	v_lshlrev_b32_e32 v0, 10, v33
	v_and_b32_e32 v0, 0xffffe000, v0
	v_or3_b32 v0, v0, v5, v2
	v_sub_u32_e32 v4, v2, v3
	v_sub_u32_e32 v69, v0, v3
	v_mov_b32_e32 v0, 0
	v_add_u32_e32 v75, v91, v3
	v_lshl_add_u64 v[86:87], v[84:85], 0, s[40:41]
	s_mov_b64 s[50:51], 0
	v_mov_b32_e32 v64, v4
	v_mov_b32_e32 v32, v90
	v_mov_b32_e32 v1, v0
	v_mov_b32_e32 v2, v0
	v_mov_b32_e32 v3, v0
	v_mov_b32_e32 v4, v0
	v_mov_b32_e32 v5, v0
	v_mov_b32_e32 v6, v0
	v_mov_b32_e32 v7, v0
	v_mov_b32_e32 v8, v0
	v_mov_b32_e32 v9, v0
	v_mov_b32_e32 v10, v0
	v_mov_b32_e32 v11, v0
	v_mov_b32_e32 v12, v0
	v_mov_b32_e32 v13, v0
	v_mov_b32_e32 v14, v0
	v_mov_b32_e32 v15, v0
	v_mov_b32_e32 v16, v0
	v_mov_b32_e32 v17, v0
	v_mov_b32_e32 v18, v0
	v_mov_b32_e32 v19, v0
	v_mov_b32_e32 v20, v0
	v_mov_b32_e32 v21, v0
	v_mov_b32_e32 v22, v0
	v_mov_b32_e32 v23, v0
	v_mov_b32_e32 v24, v0
	v_mov_b32_e32 v25, v0
	v_mov_b32_e32 v26, v0
	v_mov_b32_e32 v27, v0
	v_mov_b32_e32 v28, v0
	v_mov_b32_e32 v29, v0
	v_mov_b32_e32 v30, v0
	v_mov_b32_e32 v31, v0
	v_readlane_b32 s1, v254, 7
	v_readlane_b32 s2, v254, 8
	v_readlane_b32 s3, v254, 9
	v_readlane_b32 s4, v254, 10
	v_readlane_b32 s5, v254, 11
	v_readlane_b32 s6, v254, 12
	v_readlane_b32 s7, v254, 13
	v_readlane_b32 s8, v254, 14
	v_readlane_b32 s9, v254, 15
	v_readlane_b32 s10, v254, 16
	v_readlane_b32 s11, v254, 17
	v_readlane_b32 s14, v254, 20
	v_readlane_b32 s15, v254, 21
	v_lshrrev_b32_e32 v164, 5, v179
	v_lshlrev_b32_e32 v164, 3, v164
	v_mov_b32_e32 v165, 0
